# mixer schedule: odd bins 64..159 run {C,P,L,P} instead of {C,P,P,L}
# speedup vs baseline: 1.0003x; 1.0003x over previous
.Lsched_cppl:
	s_cmp_eq_u32 s40, 2
	s_cselect_b32 s4, 0, 2
	s_cmp_lg_u32 s40, 0
	s_cselect_b32 s64, s4, 1
	v_readlane_b32 s5, v255, 0
	s_nop 0
	s_cmp_eq_u32 s40, 1
	s_cselect_b32 s4, 2, 3
	s_add_i32 s5, s5, s4
	s_bitcmp1_b32 s40, 0
	s_cselect_b32 s4, s5, s22
